# strategy 8: NSA selected tile - the 16 accumulator copies interleaved into the serial row-max chain and used as the permlane hazard fill
# speedup vs baseline: 1.0162x; 1.0037x over previous
; DI float ex2(float x) { return __builtin_amdgcn_exp2f(x); }
; #define SB0 __builtin_amdgcn_sched_barrier(0)
; DI void nsa_S(f32x4 (&s)[4], const char* Kb, const char* Vb, const bf16x8 (&qf)[4], bf16x8 (&v0)[4], int lr, int quad) {
;   bf16x8 k0[4], k1[4], k2[4], k3[4];
;   ldk4(k0, Kb, 0, lr, quad); SB0;
;   ldk4(k1, Kb, 1, lr, quad); s[0] = mma4(k0, qf); SB0;
;   ldk4(k2, Kb, 2, lr, quad); s[1] = mma4(k1, qf); SB0;
;   ldk4(k3, Kb, 3, lr, quad); s[2] = mma4(k2, qf); SB0;
;   ldv4(v0, Vb, 0, lr, quad); s[3] = mma4(k3, qf); SB0;
; }
; template <bool MASKED, class MF>
; DI void flash_update(f32x4 (&s)[4], float scl, float& mx, float& ls, f32x4 (&o)[8], MF maskfn, bool lane_on) {
;   float tmax = -1e30f;
; #pragma unroll
;   for (int kt = 0; kt < 4; ++kt)
; #pragma unroll
;     for (int i = 0; i < 4; ++i) {
;       if (MASKED) { if (maskfn(kt, i)) s[kt][i] = -1e30f; }
;       tmax = fmaxf(tmax, s[kt][i]);
;     }
;   tmax = rowmax4(tmax);
;   if (!lane_on) tmax = -1e30f;
;   const float th = 8.f / scl;
;   if (__any(tmax > mx + th)) {
;     const float mnew = fmaxf(mx, tmax);
;     const float alpha = ex2((mx - mnew) * scl);
;     ls *= alpha;
; #pragma unroll
;     for (int dt = 0; dt < 8; ++dt) o[dt] *= alpha;
;     mx = mnew;
;   }
.LBB0_817:
	s_or_b32 s59, s48, s56
	s_cmp_gt_u32 s59, s2
	s_cbranch_scc1 .LBB0_816
	s_and_b32 s38, s59, 31
	s_waitcnt lgkmcnt(0)
	v_mov_b32_e32 v0, v172
	v_lshrrev_b32_e32 v1, s59, v0
	v_bfe_u32 v0, v0, s38, 1
	v_and_b32_e32 v1, 1, v1
	v_cmp_ne_u32_e32 vcc, 0, v0
	v_cmp_eq_u32_e64 s[38:39], 1, v1
	s_cbranch_vccz .LBB0_829
	s_lshl_b32 s48, s48, 15
	s_add_i32 s58, s57, s48
	v_add_u32_e32 v8, s58, v234
	v_add_u32_e32 v122, v8, v235
	v_add_u32_e32 v124, v8, v237
	v_add_u32_e32 v123, v8, v236
	ds_read_b128 v[0:3], v122
	ds_read_b128 v[4:7], v123
	v_add_u32_e32 v125, v8, v238
	ds_read_b128 v[8:11], v124
	ds_read_b128 v[12:15], v125
	ds_read_b128 v[98:101], v122 offset:4096
	ds_read_b128 v[102:105], v123 offset:4096
	ds_read_b128 v[106:109], v124 offset:4096
	ds_read_b128 v[110:113], v125 offset:4096
	s_waitcnt lgkmcnt(7)
	v_mfma_f32_16x16x32_bf16 v[142:145], v[0:3], v[18:21], 0
	s_waitcnt lgkmcnt(6)
	v_mfma_f32_16x16x32_bf16 v[142:145], v[4:7], v[22:25], v[142:145]
	s_waitcnt lgkmcnt(5)
	v_mfma_f32_16x16x32_bf16 v[142:145], v[8:11], v[26:29], v[142:145]
	s_waitcnt lgkmcnt(4)
	v_mfma_f32_16x16x32_bf16 v[114:117], v[12:15], v[30:33], v[142:145]
	ds_read_b128 v[0:3], v122 offset:8192
	ds_read_b128 v[4:7], v123 offset:8192
	ds_read_b128 v[8:11], v124 offset:8192
	ds_read_b128 v[12:15], v125 offset:8192
	s_waitcnt lgkmcnt(7)
	v_mfma_f32_16x16x32_bf16 v[98:101], v[98:101], v[18:21], 0
	s_waitcnt lgkmcnt(6)
	v_mfma_f32_16x16x32_bf16 v[98:101], v[102:105], v[22:25], v[98:101]
	s_waitcnt lgkmcnt(5)
	v_mfma_f32_16x16x32_bf16 v[98:101], v[106:109], v[26:29], v[98:101]
	s_waitcnt lgkmcnt(4)
	v_mfma_f32_16x16x32_bf16 v[118:121], v[110:113], v[30:33], v[98:101]
	s_nop 0
	ds_read_b128 v[126:129], v122 offset:12288
	ds_read_b128 v[130:133], v123 offset:12288
	ds_read_b128 v[134:137], v124 offset:12288
	ds_read_b128 v[138:141], v125 offset:12288
	s_waitcnt lgkmcnt(7)
	v_mfma_f32_16x16x32_bf16 v[142:145], v[0:3], v[18:21], 0
	s_waitcnt lgkmcnt(6)
	v_mfma_f32_16x16x32_bf16 v[142:145], v[4:7], v[22:25], v[142:145]
	s_waitcnt lgkmcnt(5)
	v_mfma_f32_16x16x32_bf16 v[142:145], v[8:11], v[26:29], v[142:145]
	s_waitcnt lgkmcnt(4)
	v_mfma_f32_16x16x32_bf16 v[122:125], v[12:15], v[30:33], v[142:145]
	v_add_u32_e32 v0, s58, v242
	v_add_u32_e32 v174, v0, v241
	ds_read_b128 v[98:101], v174 offset:16384
	ds_read_b128 v[102:105], v174 offset:18432
	ds_read_b128 v[106:109], v174 offset:20480
	ds_read_b128 v[110:113], v174 offset:22528
	s_waitcnt lgkmcnt(7)
	v_mfma_f32_16x16x32_bf16 v[0:3], v[126:129], v[18:21], 0
	s_waitcnt lgkmcnt(6)
	v_mfma_f32_16x16x32_bf16 v[0:3], v[130:133], v[22:25], v[0:3]
	s_waitcnt lgkmcnt(5)
	v_mfma_f32_16x16x32_bf16 v[0:3], v[134:137], v[26:29], v[0:3]
	s_waitcnt lgkmcnt(4)
	v_mfma_f32_16x16x32_bf16 v[126:129], v[138:141], v[30:33], v[0:3]
	s_nop 0
	s_mov_b64 s[48:49], -1
	s_cmp_lg_u32 s59, s2
	v_add_f32_e32 v176, 0x427af232, v173
	s_cbranch_scc0 .LBB0_823
	v_mov_b64_e32 v[160:161], v[68:69]
	v_mov_b64_e32 v[156:157], v[72:73]
	v_max3_f32 v0, v114, s41, v115
	v_mov_b64_e32 v[152:153], v[76:77]
	v_max3_f32 v0, v0, v116, v117
	v_mov_b64_e32 v[148:149], v[80:81]
	v_max3_f32 v0, v0, v118, v119
	v_mov_b64_e32 v[144:145], v[84:85]
	v_max3_f32 v0, v0, v120, v121
	v_mov_b64_e32 v[140:141], v[88:89]
	v_max3_f32 v0, v0, v122, v123
	v_mov_b64_e32 v[136:137], v[92:93]
	v_max3_f32 v0, v0, v124, v125
	v_mov_b64_e32 v[132:133], v[96:97]
	v_max3_f32 v0, v0, v126, v127
	v_mov_b64_e32 v[158:159], v[66:67]
	v_max3_f32 v0, v0, v128, v129
	v_mov_b32_e32 v1, v0
	v_mov_b64_e32 v[154:155], v[70:71]
	v_mov_b64_e32 v[150:151], v[74:75]
	v_permlane16_swap_b32_e32 v0, v1
	v_max_f32_e32 v0, v0, v1
	v_mov_b32_e32 v1, v0
	v_mov_b64_e32 v[146:147], v[78:79]
	v_mov_b64_e32 v[142:143], v[82:83]
	v_permlane32_swap_b32_e32 v0, v1
	v_max_f32_e32 v0, v0, v1
	v_cndmask_b32_e64 v0, v231, v0, s[38:39]
	v_mov_b64_e32 v[138:139], v[86:87]
	v_mov_b64_e32 v[134:135], v[90:91]
	v_mov_b64_e32 v[130:131], v[94:95]
	v_cmp_gt_f32_e32 vcc, v0, v176
	v_mov_b32_e32 v177, v170
	v_mov_b32_e32 v175, v173
	s_cbranch_vccz .LBB0_822
	v_max_f32_e32 v0, v0, v0
	v_max_f32_e32 v1, v173, v173
	v_max_f32_e32 v175, v1, v0
	v_sub_f32_e32 v0, v173, v175
	v_mul_f32_e32 v0, 0x3e0293ee, v0
	v_exp_f32_e32 v0, v0
	s_nop 0
	v_mul_f32_e32 v177, v170, v0
	v_pk_mul_f32 v[132:133], v[96:97], v[0:1] op_sel_hi:[1,0]
	v_pk_mul_f32 v[130:131], v[94:95], v[0:1] op_sel_hi:[1,0]
	v_pk_mul_f32 v[136:137], v[92:93], v[0:1] op_sel_hi:[1,0]
	v_pk_mul_f32 v[134:135], v[90:91], v[0:1] op_sel_hi:[1,0]
	v_pk_mul_f32 v[140:141], v[88:89], v[0:1] op_sel_hi:[1,0]
	v_pk_mul_f32 v[138:139], v[86:87], v[0:1] op_sel_hi:[1,0]
	v_pk_mul_f32 v[144:145], v[84:85], v[0:1] op_sel_hi:[1,0]
	v_pk_mul_f32 v[142:143], v[82:83], v[0:1] op_sel_hi:[1,0]
	v_pk_mul_f32 v[148:149], v[80:81], v[0:1] op_sel_hi:[1,0]
	v_pk_mul_f32 v[146:147], v[78:79], v[0:1] op_sel_hi:[1,0]
	v_pk_mul_f32 v[152:153], v[76:77], v[0:1] op_sel_hi:[1,0]
	v_pk_mul_f32 v[150:151], v[74:75], v[0:1] op_sel_hi:[1,0]
	v_pk_mul_f32 v[156:157], v[72:73], v[0:1] op_sel_hi:[1,0]
	v_pk_mul_f32 v[154:155], v[70:71], v[0:1] op_sel_hi:[1,0]
	v_pk_mul_f32 v[160:161], v[68:69], v[0:1] op_sel_hi:[1,0]
	v_pk_mul_f32 v[158:159], v[66:67], v[0:1] op_sel_hi:[1,0]
